# V s0 reads early, s_not mask inversions, global prefetch issue after the first four MFMAs
# baseline (speedup 1.0000x reference)
.LBB0_542:
	s_cmp_gt_u32 s52, s51
	s_cbranch_scc1 .Lh1_skip
	s_mul_i32 s61, s25, 0x2200
	s_and_b32 s42, s52, 2
	s_mulk_i32 s42, 0x3400
	v_add_u32_e32 v0, s42, v160
	v_add_u32_e32 v242, s61, v161
	v_add_u32_e32 v163, 0xe000, v242
	v_add_u32_e32 v242, 0xd000, v242
	ds_read_b128 v[82:85], v0 offset:13312
	ds_read_b128 v[98:101], v0 offset:19968
	ds_read2_b64 v[238:241], v242 offset0:0 offset1:2
	ds_read2_b64 v[234:237], v163 offset0:32 offset1:34
	ds_read_b128 v[164:167], v0 offset:13344
	ds_read_b128 v[168:171], v0 offset:20000
	ds_read_b128 v[172:175], v0 offset:13376
	ds_read_b128 v[176:179], v0 offset:20032
	ds_read_b128 v[180:183], v0 offset:13408
	ds_read_b128 v[184:187], v0 offset:20064
	ds_read_b128 v[188:191], v0 offset:13440
	ds_read_b128 v[192:195], v0 offset:20096
	ds_read_b128 v[196:199], v0 offset:13472
	ds_read_b128 v[220:223], v0 offset:20128
	v_exp_f32_e32 v50, v50
	v_exp_f32_e32 v51, v51
	v_exp_f32_e32 v52, v52
	v_exp_f32_e32 v53, v53
	v_exp_f32_e32 v54, v54
	v_exp_f32_e32 v55, v55
	v_exp_f32_e32 v56, v56
	v_exp_f32_e32 v57, v57
	s_waitcnt lgkmcnt(13)
	v_mfma_f32_32x32x16_bf16 v[82:97], v[82:85], v[122:125], 0
	v_cvt_pk_bf16_f32 v224, v50, v51
	v_cvt_pk_bf16_f32 v225, v52, v53
	v_cvt_pk_bf16_f32 v226, v54, v55
	v_cvt_pk_bf16_f32 v227, v56, v57
	v_exp_f32_e32 v58, v58
	v_add_f32_e32 v200, v50, v51
	s_waitcnt lgkmcnt(12)
	v_mfma_f32_32x32x16_bf16 v[98:113], v[98:101], v[122:125], 0
	v_exp_f32_e32 v59, v59
	v_exp_f32_e32 v60, v60
	v_add_f32_e32 v201, v52, v53
	v_exp_f32_e32 v61, v61
	s_waitcnt lgkmcnt(9)
	v_mfma_f32_32x32x16_bf16 v[82:97], v[164:167], v[126:129], v[82:97]
	v_exp_f32_e32 v62, v62
	v_add_f32_e32 v200, v200, v54
	v_exp_f32_e32 v63, v63
	v_add_f32_e32 v201, v201, v55
	v_exp_f32_e32 v64, v64
	s_waitcnt lgkmcnt(8)
	v_mfma_f32_32x32x16_bf16 v[98:113], v[168:171], v[126:129], v[98:113]
	ds_read2_b64 v[164:167], v242 offset0:4 offset1:6
	ds_read2_b64 v[168:171], v163 offset0:36 offset1:38
	v_add_f32_e32 v200, v200, v56
	v_exp_f32_e32 v65, v65
	v_add_f32_e32 v201, v201, v57
	v_cvt_pk_bf16_f32 v228, v58, v59
	v_cvt_pk_bf16_f32 v229, v60, v61
	s_add_i32 s60, s52, 3
	s_cmp_lt_u32 s60, s48
	s_cselect_b64 s[58:59], -1, 0
	s_cmp_ge_u32 s60, s48
	s_cbranch_scc1 .Lp1a_546
	s_waitcnt vmcnt(0)
	v_lshl_add_u64 v[2:3], s[54:55], 0, v[154:155]
	v_add_co_u32_e32 v2, vcc, 0xbe09000, v2
	s_nop 1
	v_addc_co_u32_e32 v3, vcc, 0, v3, vcc
	global_load_dwordx4 v[2:5], v[2:3], off
	s_and_saveexec_b64 s[42:43], s[40:41]
	s_cbranch_execz .Lp1a_545
	v_lshl_add_u64 v[10:11], s[54:55], 0, v[152:153]
	v_add_co_u32_e32 v10, vcc, 0xbe09000, v10
	s_nop 1
	v_addc_co_u32_e32 v11, vcc, 0, v11, vcc
	global_load_dwordx4 v[10:13], v[10:11], off

.Lp1a_end:
	s_waitcnt lgkmcnt(13)
	v_mfma_f32_32x32x16_bf16 v[18:33], v[238:241], v[224:227], v[18:33]
	v_cvt_pk_bf16_f32 v230, v62, v63
	v_cvt_pk_bf16_f32 v231, v64, v65
	v_exp_f32_e32 v66, v66
	v_add_f32_e32 v200, v200, v58
	v_exp_f32_e32 v67, v67
	v_add_f32_e32 v201, v201, v59
	s_waitcnt lgkmcnt(12)
	v_mfma_f32_32x32x16_bf16 v[34:49], v[234:237], v[224:227], v[34:49]
	v_exp_f32_e32 v68, v68
	v_add_f32_e32 v200, v200, v60
	v_exp_f32_e32 v69, v69
	v_add_f32_e32 v201, v201, v61
	v_exp_f32_e32 v70, v70
	s_waitcnt lgkmcnt(9)
	v_mfma_f32_32x32x16_bf16 v[82:97], v[172:175], v[134:137], v[82:97]
	v_add_f32_e32 v200, v200, v62
	v_exp_f32_e32 v71, v71
	v_add_f32_e32 v201, v201, v63
	v_exp_f32_e32 v72, v72
	v_add_f32_e32 v200, v200, v64
	s_waitcnt lgkmcnt(8)
	v_mfma_f32_32x32x16_bf16 v[98:113], v[176:179], v[134:137], v[98:113]
	ds_read2_b64 v[172:175], v242 offset0:8 offset1:10
	ds_read2_b64 v[176:179], v163 offset0:40 offset1:42
	v_exp_f32_e32 v73, v73
	v_add_f32_e32 v201, v201, v65
	v_cvt_pk_bf16_f32 v224, v66, v67
	v_cvt_pk_bf16_f32 v225, v68, v69
	v_cvt_pk_bf16_f32 v226, v70, v71
	s_waitcnt lgkmcnt(3)
	v_mfma_f32_32x32x16_bf16 v[18:33], v[164:167], v[228:231], v[18:33]
	v_cvt_pk_bf16_f32 v227, v72, v73
	v_exp_f32_e32 v74, v74
	v_add_f32_e32 v200, v200, v66
	v_exp_f32_e32 v75, v75
	v_add_f32_e32 v201, v201, v67
	s_waitcnt lgkmcnt(2)
	v_mfma_f32_32x32x16_bf16 v[34:49], v[168:171], v[228:231], v[34:49]
	v_exp_f32_e32 v76, v76
	v_add_f32_e32 v200, v200, v68
	v_exp_f32_e32 v77, v77
	v_add_f32_e32 v201, v201, v69
	v_exp_f32_e32 v78, v78
	s_waitcnt lgkmcnt(9)
	v_mfma_f32_32x32x16_bf16 v[82:97], v[180:183], v[138:141], v[82:97]
	v_add_f32_e32 v200, v200, v70
	v_exp_f32_e32 v79, v79
	v_add_f32_e32 v201, v201, v71
	v_exp_f32_e32 v80, v80
	v_add_f32_e32 v200, v200, v72
	s_waitcnt lgkmcnt(8)
	v_mfma_f32_32x32x16_bf16 v[98:113], v[184:187], v[138:141], v[98:113]
	ds_read2_b64 v[180:183], v242 offset0:12 offset1:14
	ds_read2_b64 v[184:187], v163 offset0:44 offset1:46
	v_exp_f32_e32 v81, v81
	v_add_f32_e32 v201, v201, v73
	v_cvt_pk_bf16_f32 v228, v74, v75
	v_cvt_pk_bf16_f32 v229, v76, v77
	v_cvt_pk_bf16_f32 v230, v78, v79
	s_waitcnt lgkmcnt(3)
	v_mfma_f32_32x32x16_bf16 v[18:33], v[172:175], v[224:227], v[18:33]
	v_cvt_pk_bf16_f32 v231, v80, v81
	v_add_f32_e32 v200, v200, v74
	v_add_f32_e32 v201, v201, v75
	v_add_f32_e32 v200, v200, v76
	v_add_f32_e32 v201, v201, v77
	v_add_f32_e32 v200, v200, v78
	v_add_f32_e32 v201, v201, v79
	v_add_f32_e32 v200, v200, v80
	s_waitcnt lgkmcnt(2)
	v_mfma_f32_32x32x16_bf16 v[34:49], v[176:179], v[224:227], v[34:49]
	v_add_f32_e32 v201, v201, v81
	v_add_f32_e32 v200, v200, v201
	v_add_f32_e32 v162, v162, v200
	s_waitcnt lgkmcnt(9)
	v_mfma_f32_32x32x16_bf16 v[82:97], v[188:191], v[142:145], v[82:97]
	s_waitcnt lgkmcnt(8)
	v_mfma_f32_32x32x16_bf16 v[98:113], v[192:195], v[142:145], v[98:113]
	s_waitcnt lgkmcnt(7)
	v_mfma_f32_32x32x16_bf16 v[82:97], v[196:199], v[146:149], v[82:97]
	s_waitcnt lgkmcnt(6)
	v_mfma_f32_32x32x16_bf16 v[98:113], v[220:223], v[146:149], v[98:113]
	s_waitcnt lgkmcnt(0)
	s_not_b64 s[42:43], s[44:45]
	s_andn2_b64 vcc, exec, s[44:45]
	s_cbranch_vccnz .Lt1a_mid
	s_and_b32 s44, s53, 2
	s_mulk_i32 s44, 0x3400
	s_add_i32 s62, s44, 0
	v_add_u32_e32 v0, s62, v151
	s_waitcnt vmcnt(0)
	ds_write_b128 v0, v[118:121]
	s_and_saveexec_b64 s[44:45], s[40:41]
	v_add_u32_e32 v0, s62, v159
	ds_write_b128 v0, v[6:9]
	s_or_b64 exec, exec, s[44:45]

.LBB0_556:
	s_add_i32 s61, s25, 1
	s_cmp_lg_u32 s25, 2
	s_cselect_b32 s25, s61, 0
	s_andn2_b64 vcc, exec, s[44:45]
	s_waitcnt lgkmcnt(0)
	s_barrier
	s_cbranch_vccnz .LBB0_572
	s_cmp_ge_u32 s52, s51
	s_cbranch_scc1 .Lh2_skip
	s_andn2_b32 s62, 2, s52
	s_mulk_i32 s62, 0x3400
	v_add_u32_e32 v0, s62, v160
	s_mul_i32 s62, s25, 0x2200
	v_add_u32_e32 v242, s62, v161
	v_add_u32_e32 v163, 0xe000, v242
	v_add_u32_e32 v242, 0xd000, v242
	ds_read_b128 v[50:53], v0 offset:0
	ds_read_b128 v[66:69], v0 offset:6656
	ds_read2_b64 v[238:241], v242 offset0:0 offset1:2
	ds_read2_b64 v[234:237], v163 offset0:32 offset1:34
	ds_read_b128 v[164:167], v0 offset:32
	ds_read_b128 v[168:171], v0 offset:6688
	ds_read_b128 v[172:175], v0 offset:64
	ds_read_b128 v[176:179], v0 offset:6720
	ds_read_b128 v[180:183], v0 offset:96
	ds_read_b128 v[184:187], v0 offset:6752
	ds_read_b128 v[188:191], v0 offset:128
	ds_read_b128 v[192:195], v0 offset:6784
	ds_read_b128 v[196:199], v0 offset:160
	ds_read_b128 v[220:223], v0 offset:6816
	v_exp_f32_e32 v82, v82
	v_exp_f32_e32 v83, v83
	v_exp_f32_e32 v84, v84
	v_exp_f32_e32 v85, v85
	v_exp_f32_e32 v86, v86
	v_exp_f32_e32 v87, v87
	v_exp_f32_e32 v88, v88
	v_exp_f32_e32 v89, v89
	s_waitcnt lgkmcnt(13)
	v_mfma_f32_32x32x16_bf16 v[50:65], v[50:53], v[122:125], 0
	v_cvt_pk_bf16_f32 v224, v82, v83
	v_cvt_pk_bf16_f32 v225, v84, v85
	v_cvt_pk_bf16_f32 v226, v86, v87
	v_cvt_pk_bf16_f32 v227, v88, v89
	v_exp_f32_e32 v90, v90
	v_add_f32_e32 v200, v82, v83
	s_waitcnt lgkmcnt(12)
	v_mfma_f32_32x32x16_bf16 v[66:81], v[66:69], v[122:125], 0
	v_exp_f32_e32 v91, v91
	v_exp_f32_e32 v92, v92
	v_add_f32_e32 v201, v84, v85
	v_exp_f32_e32 v93, v93
	s_waitcnt lgkmcnt(9)
	v_mfma_f32_32x32x16_bf16 v[50:65], v[164:167], v[126:129], v[50:65]
	v_exp_f32_e32 v94, v94
	v_add_f32_e32 v200, v200, v86
	v_exp_f32_e32 v95, v95
	v_add_f32_e32 v201, v201, v87
	v_exp_f32_e32 v96, v96
	s_waitcnt lgkmcnt(8)
	v_mfma_f32_32x32x16_bf16 v[66:81], v[168:171], v[126:129], v[66:81]
	ds_read2_b64 v[164:167], v242 offset0:4 offset1:6
	ds_read2_b64 v[168:171], v163 offset0:36 offset1:38
	v_add_f32_e32 v200, v200, v88
	v_exp_f32_e32 v97, v97
	v_add_f32_e32 v201, v201, v89
	v_cvt_pk_bf16_f32 v228, v90, v91
	v_cvt_pk_bf16_f32 v229, v92, v93
	s_cmp_ge_u32 s52, s5
	s_cbranch_scc1 .Lp2a_561
	s_waitcnt vmcnt(0)
	v_lshl_add_u64 v[118:119], s[54:55], 0, v[154:155]
	v_add_co_u32_e32 v118, vcc, 0xbe0c000, v118
	s_nop 1
	v_addc_co_u32_e32 v119, vcc, 0, v119, vcc
	global_load_dwordx4 v[118:121], v[118:119], off
	s_and_saveexec_b64 s[44:45], s[40:41]
	s_cbranch_execz .Lp2a_560
	v_lshl_add_u64 v[6:7], s[54:55], 0, v[152:153]
	v_add_co_u32_e32 v6, vcc, 0xbe0c000, v6
	s_nop 1
	v_addc_co_u32_e32 v7, vcc, 0, v7, vcc
	global_load_dwordx4 v[6:9], v[6:7], off

.Lp2a_end:
	s_waitcnt lgkmcnt(13)
	v_mfma_f32_32x32x16_bf16 v[18:33], v[238:241], v[224:227], v[18:33]
	v_cvt_pk_bf16_f32 v230, v94, v95
	v_cvt_pk_bf16_f32 v231, v96, v97
	v_exp_f32_e32 v98, v98
	v_add_f32_e32 v200, v200, v90
	v_exp_f32_e32 v99, v99
	v_add_f32_e32 v201, v201, v91
	s_waitcnt lgkmcnt(12)
	v_mfma_f32_32x32x16_bf16 v[34:49], v[234:237], v[224:227], v[34:49]
	v_exp_f32_e32 v100, v100
	v_add_f32_e32 v200, v200, v92
	v_exp_f32_e32 v101, v101
	v_add_f32_e32 v201, v201, v93
	v_exp_f32_e32 v102, v102
	s_waitcnt lgkmcnt(9)
	v_mfma_f32_32x32x16_bf16 v[50:65], v[172:175], v[134:137], v[50:65]
	v_add_f32_e32 v200, v200, v94
	v_exp_f32_e32 v103, v103
	v_add_f32_e32 v201, v201, v95
	v_exp_f32_e32 v104, v104
	v_add_f32_e32 v200, v200, v96
	s_waitcnt lgkmcnt(8)
	v_mfma_f32_32x32x16_bf16 v[66:81], v[176:179], v[134:137], v[66:81]
	ds_read2_b64 v[172:175], v242 offset0:8 offset1:10
	ds_read2_b64 v[176:179], v163 offset0:40 offset1:42
	v_exp_f32_e32 v105, v105
	v_add_f32_e32 v201, v201, v97
	v_cvt_pk_bf16_f32 v224, v98, v99
	v_cvt_pk_bf16_f32 v225, v100, v101
	v_cvt_pk_bf16_f32 v226, v102, v103
	s_waitcnt lgkmcnt(3)
	v_mfma_f32_32x32x16_bf16 v[18:33], v[164:167], v[228:231], v[18:33]
	v_cvt_pk_bf16_f32 v227, v104, v105
	v_exp_f32_e32 v106, v106
	v_add_f32_e32 v200, v200, v98
	v_exp_f32_e32 v107, v107
	v_add_f32_e32 v201, v201, v99
	s_waitcnt lgkmcnt(2)
	v_mfma_f32_32x32x16_bf16 v[34:49], v[168:171], v[228:231], v[34:49]
	v_exp_f32_e32 v108, v108
	v_add_f32_e32 v200, v200, v100
	v_exp_f32_e32 v109, v109
	v_add_f32_e32 v201, v201, v101
	v_exp_f32_e32 v110, v110
	s_waitcnt lgkmcnt(9)
	v_mfma_f32_32x32x16_bf16 v[50:65], v[180:183], v[138:141], v[50:65]
	v_add_f32_e32 v200, v200, v102
	v_exp_f32_e32 v111, v111
	v_add_f32_e32 v201, v201, v103
	v_exp_f32_e32 v112, v112
	v_add_f32_e32 v200, v200, v104
	s_waitcnt lgkmcnt(8)
	v_mfma_f32_32x32x16_bf16 v[66:81], v[184:187], v[138:141], v[66:81]
	ds_read2_b64 v[180:183], v242 offset0:12 offset1:14
	ds_read2_b64 v[184:187], v163 offset0:44 offset1:46
	v_exp_f32_e32 v113, v113
	v_add_f32_e32 v201, v201, v105
	v_cvt_pk_bf16_f32 v228, v106, v107
	v_cvt_pk_bf16_f32 v229, v108, v109
	v_cvt_pk_bf16_f32 v230, v110, v111
	s_waitcnt lgkmcnt(3)
	v_mfma_f32_32x32x16_bf16 v[18:33], v[172:175], v[224:227], v[18:33]
	v_cvt_pk_bf16_f32 v231, v112, v113
	v_add_f32_e32 v200, v200, v106
	v_add_f32_e32 v201, v201, v107
	v_add_f32_e32 v200, v200, v108
	v_add_f32_e32 v201, v201, v109
	v_add_f32_e32 v200, v200, v110
	v_add_f32_e32 v201, v201, v111
	v_add_f32_e32 v200, v200, v112
	s_waitcnt lgkmcnt(2)
	v_mfma_f32_32x32x16_bf16 v[34:49], v[176:179], v[224:227], v[34:49]
	v_add_f32_e32 v201, v201, v113
	v_add_f32_e32 v200, v200, v201
	v_add_f32_e32 v162, v162, v200
	s_waitcnt lgkmcnt(9)
	v_mfma_f32_32x32x16_bf16 v[50:65], v[188:191], v[142:145], v[50:65]
	s_waitcnt lgkmcnt(8)
	v_mfma_f32_32x32x16_bf16 v[66:81], v[192:195], v[142:145], v[66:81]
	s_waitcnt lgkmcnt(7)
	v_mfma_f32_32x32x16_bf16 v[50:65], v[196:199], v[146:149], v[50:65]
	s_waitcnt lgkmcnt(6)
	v_mfma_f32_32x32x16_bf16 v[66:81], v[220:223], v[146:149], v[66:81]
	s_waitcnt lgkmcnt(0)
	s_mul_i32 s58, s25, 0x2200
	s_and_b64 vcc, exec, s[44:45]
	s_cbranch_vccnz .Lt2a_mid
	s_and_b32 s44, s60, 3
	s_mulk_i32 s44, 0x3400
	s_add_i32 s52, s44, 0
	v_add_u32_e32 v0, s52, v151
	s_waitcnt vmcnt(0)
	ds_write_b128 v0, v[2:5]
	s_and_saveexec_b64 s[44:45], s[40:41]
	v_add_u32_e32 v0, s52, v159
	ds_write_b128 v0, v[10:13]
	s_or_b64 exec, exec, s[44:45]
